# v16 + Resid epilogue: the 8 per-row sum-of-squares atomics deferred to the end of the epilogue (in-order vmcnt no longer waits on them mid-epilogue)
# speedup vs baseline: 1.0151x; 1.0151x over previous
.LBB0_690:
	s_add_u32 s0, s58, s85
	s_addc_u32 s3, s59, s84
	s_add_u32 s58, s0, 0x310000
	s_addc_u32 s59, s3, 0
	s_and_b64 vcc, exec, s[6:7]
	s_cbranch_vccnz .LBB0_694
	v_cmp_lt_i32_e32 vcc, v227, v222
	s_nop 1
	v_cndmask_b32_e32 v146, v221, v227, vcc
	v_lshlrev_b32_e32 v146, 2, v146
	ds_bpermute_b32 v146, v146, v166
	v_cmp_lt_i32_e32 vcc, v228, v222
	s_waitcnt lgkmcnt(0)
	v_add_f32_e32 v146, v166, v146
	v_cndmask_b32_e32 v147, v221, v228, vcc
	v_lshlrev_b32_e32 v147, 2, v147
	ds_bpermute_b32 v147, v147, v146
	s_waitcnt lgkmcnt(0)
	v_add_f32_e32 v244, v146, v147
.LBB0_693:
.LBB0_694:
	s_waitcnt vmcnt(1)
	v_lshlrev_b32_e32 v146, 16, v174
	s_waitcnt lgkmcnt(0)
	v_and_b32_e32 v147, 0xffff0000, v174
	v_lshlrev_b32_e32 v148, 16, v175
	v_and_b32_e32 v149, 0xffff0000, v175
	v_lshlrev_b32_e32 v150, 16, v176
	v_and_b32_e32 v151, 0xffff0000, v176
	v_lshlrev_b32_e32 v152, 16, v177
	v_and_b32_e32 v153, 0xffff0000, v177
	v_pk_mul_f32 v[146:147], v[90:91], v[146:147]
	v_pk_mul_f32 v[148:149], v[92:93], v[148:149]
	v_pk_mul_f32 v[150:151], v[94:95], v[150:151]
	v_pk_mul_f32 v[152:153], v[96:97], v[152:153]
	v_pk_fma_f32 v[144:145], v[144:145], v[206:207], v[148:149]
	v_pk_fma_f32 v[142:143], v[142:143], v[208:209], v[146:147]
	v_pk_fma_f32 v[140:141], v[140:141], v[202:203], v[152:153]
	v_pk_fma_f32 v[138:139], v[138:139], v[204:205], v[150:151]
	s_and_b64 vcc, exec, s[6:7]
	s_mov_b64 s[20:21], -1
	s_cbranch_vccnz .LBB0_696
	v_mov_b32_e32 v148, v143
	v_mov_b32_e32 v149, v139
	v_mov_b32_e32 v146, v142
	v_mov_b32_e32 v147, v138
	v_pk_mul_f32 v[148:149], v[148:149], v[148:149]
	v_mov_b32_e32 v150, v145
	v_mov_b32_e32 v151, v141
	v_pk_fma_f32 v[146:147], v[146:147], v[146:147], v[148:149]
	v_mov_b32_e32 v148, v144
	v_mov_b32_e32 v149, v140
	v_pk_mul_f32 v[150:151], v[150:151], v[150:151]
	v_pk_mul_f32 v[166:167], v[68:69], v[140:141]
	v_pk_fma_f32 v[148:149], v[148:149], v[148:149], v[150:151]
	v_pk_mul_f32 v[150:151], v[70:71], v[142:143]
	v_pk_add_f32 v[146:147], v[146:147], v[148:149]
	v_pk_mul_f32 v[152:153], v[66:67], v[138:139]
	v_add_f32_e32 v148, v146, v147
	v_pk_mul_f32 v[146:147], v[72:73], v[144:145]
	v_cvt_pk_bf16_f32 v150, v150, v151
	v_cvt_pk_bf16_f32 v151, v146, v147
	v_cvt_pk_bf16_f32 v152, v152, v153
	v_cvt_pk_bf16_f32 v153, v166, v167
	s_mov_b64 s[20:21], 0
	global_store_dwordx4 v[212:213], v[150:153], off

.LBB0_703:
	v_cmp_lt_i32_e32 vcc, v227, v222
	s_nop 1
	v_cndmask_b32_e32 v130, v221, v227, vcc
	v_lshlrev_b32_e32 v130, 2, v130
	ds_bpermute_b32 v130, v130, v138
	v_cmp_lt_i32_e32 vcc, v228, v222
	s_waitcnt lgkmcnt(0)
	v_add_f32_e32 v130, v138, v130
	v_cndmask_b32_e32 v131, v221, v228, vcc
	v_lshlrev_b32_e32 v131, 2, v131
	ds_bpermute_b32 v131, v131, v130
	s_waitcnt lgkmcnt(0)
	v_add_f32_e32 v245, v130, v131
.LBB0_705:
.LBB0_706:
	v_or_b32_e32 v148, 32, v200
	v_ashrrev_i32_e32 v149, 31, v148
	s_waitcnt lgkmcnt(0)
	v_lshlrev_b64 v[130:131], 11, v[148:149]
	v_lshl_add_u64 v[146:147], v[210:211], 0, v[130:131]
	v_or_b32_e32 v144, 48, v200
	global_load_dwordx4 v[150:153], v[146:147], off
	v_ashrrev_i32_e32 v145, 31, v144
	v_lshlrev_b64 v[130:131], 11, v[144:145]
	v_lshl_add_u64 v[142:143], v[210:211], 0, v[130:131]
	global_load_dwordx4 v[138:141], v[146:147], off offset:256
	global_load_dwordx4 v[134:137], v[142:143], off
	global_load_dwordx4 v[130:133], v[142:143], off offset:256
	s_and_b64 vcc, exec, s[6:7]
	s_mov_b64 s[20:21], -1
	s_waitcnt vmcnt(3)
	v_lshlrev_b32_e32 v162, 16, v150
	v_and_b32_e32 v163, 0xffff0000, v150
	v_lshlrev_b32_e32 v150, 16, v151
	v_and_b32_e32 v151, 0xffff0000, v151
	v_lshlrev_b32_e32 v164, 16, v152
	v_and_b32_e32 v165, 0xffff0000, v152
	v_lshlrev_b32_e32 v152, 16, v153
	v_and_b32_e32 v153, 0xffff0000, v153
	v_pk_mul_f32 v[162:163], v[90:91], v[162:163]
	v_pk_mul_f32 v[150:151], v[92:93], v[150:151]
	v_pk_mul_f32 v[164:165], v[94:95], v[164:165]
	v_pk_mul_f32 v[152:153], v[96:97], v[152:153]
	v_pk_fma_f32 v[128:129], v[128:129], v[206:207], v[150:151]
	v_pk_fma_f32 v[126:127], v[126:127], v[208:209], v[162:163]
	v_pk_fma_f32 v[124:125], v[124:125], v[202:203], v[152:153]
	v_pk_fma_f32 v[122:123], v[122:123], v[204:205], v[164:165]
	s_cbranch_vccnz .LBB0_708
	v_mov_b32_e32 v152, v127
	v_mov_b32_e32 v153, v123
	v_mov_b32_e32 v150, v126
	v_mov_b32_e32 v151, v122
	v_pk_mul_f32 v[152:153], v[152:153], v[152:153]
	v_mov_b32_e32 v162, v129
	v_mov_b32_e32 v163, v125
	v_pk_fma_f32 v[150:151], v[150:151], v[150:151], v[152:153]
	v_mov_b32_e32 v152, v128
	v_mov_b32_e32 v153, v124
	v_pk_mul_f32 v[162:163], v[162:163], v[162:163]
	v_pk_mul_f32 v[166:167], v[68:69], v[124:125]
	v_pk_fma_f32 v[152:153], v[152:153], v[152:153], v[162:163]
	v_pk_mul_f32 v[162:163], v[70:71], v[126:127]
	v_pk_add_f32 v[150:151], v[150:151], v[152:153]
	v_pk_mul_f32 v[152:153], v[72:73], v[128:129]
	v_pk_mul_f32 v[164:165], v[66:67], v[122:123]
	v_add_f32_e32 v150, v150, v151
	v_cvt_pk_bf16_f32 v162, v162, v163
	v_cvt_pk_bf16_f32 v163, v152, v153
	v_cvt_pk_bf16_f32 v164, v164, v165
	v_cvt_pk_bf16_f32 v165, v166, v167
	s_mov_b64 s[20:21], 0
	global_store_dwordx4 v[146:147], v[162:165], off

.LBB0_715:
	v_cmp_lt_i32_e32 vcc, v227, v222
	s_nop 1
	v_cndmask_b32_e32 v114, v221, v227, vcc
	v_lshlrev_b32_e32 v114, 2, v114
	ds_bpermute_b32 v114, v114, v122
	v_cmp_lt_i32_e32 vcc, v228, v222
	s_waitcnt lgkmcnt(0)
	v_add_f32_e32 v114, v122, v114
	v_cndmask_b32_e32 v115, v221, v228, vcc
	v_lshlrev_b32_e32 v115, 2, v115
	ds_bpermute_b32 v115, v115, v114
	s_waitcnt lgkmcnt(0)
	v_add_f32_e32 v246, v114, v115
.LBB0_717:
.LBB0_718:
	s_waitcnt vmcnt(1)
	v_lshlrev_b32_e32 v114, 16, v134
	s_waitcnt lgkmcnt(0)
	v_and_b32_e32 v115, 0xffff0000, v134
	v_lshlrev_b32_e32 v116, 16, v135
	v_and_b32_e32 v117, 0xffff0000, v135
	v_lshlrev_b32_e32 v118, 16, v136
	v_and_b32_e32 v119, 0xffff0000, v136
	v_lshlrev_b32_e32 v120, 16, v137
	v_and_b32_e32 v121, 0xffff0000, v137
	v_pk_mul_f32 v[114:115], v[90:91], v[114:115]
	v_pk_mul_f32 v[116:117], v[92:93], v[116:117]
	v_pk_mul_f32 v[118:119], v[94:95], v[118:119]
	v_pk_mul_f32 v[120:121], v[96:97], v[120:121]
	v_pk_fma_f32 v[112:113], v[112:113], v[206:207], v[116:117]
	v_pk_fma_f32 v[110:111], v[110:111], v[208:209], v[114:115]
	v_pk_fma_f32 v[108:109], v[108:109], v[202:203], v[120:121]
	v_pk_fma_f32 v[106:107], v[106:107], v[204:205], v[118:119]
	s_and_b64 vcc, exec, s[6:7]
	s_mov_b64 s[20:21], -1
	s_cbranch_vccnz .LBB0_720
	v_mov_b32_e32 v116, v111
	v_mov_b32_e32 v117, v107
	v_mov_b32_e32 v114, v110
	v_mov_b32_e32 v115, v106
	v_pk_mul_f32 v[116:117], v[116:117], v[116:117]
	v_mov_b32_e32 v118, v113
	v_mov_b32_e32 v119, v109
	v_pk_fma_f32 v[114:115], v[114:115], v[114:115], v[116:117]
	v_mov_b32_e32 v116, v112
	v_mov_b32_e32 v117, v108
	v_pk_mul_f32 v[118:119], v[118:119], v[118:119]
	v_pk_mul_f32 v[122:123], v[68:69], v[108:109]
	v_pk_fma_f32 v[116:117], v[116:117], v[116:117], v[118:119]
	v_pk_mul_f32 v[118:119], v[70:71], v[110:111]
	v_pk_add_f32 v[114:115], v[114:115], v[116:117]
	v_pk_mul_f32 v[120:121], v[66:67], v[106:107]
	v_add_f32_e32 v116, v114, v115
	v_pk_mul_f32 v[114:115], v[72:73], v[112:113]
	v_cvt_pk_bf16_f32 v118, v118, v119
	v_cvt_pk_bf16_f32 v119, v114, v115
	v_cvt_pk_bf16_f32 v120, v120, v121
	v_cvt_pk_bf16_f32 v121, v122, v123
	s_mov_b64 s[20:21], 0
	global_store_dwordx4 v[142:143], v[118:121], off

.LBB0_727:
	v_cmp_lt_i32_e32 vcc, v227, v222
	s_nop 1
	v_cndmask_b32_e32 v98, v221, v227, vcc
	v_lshlrev_b32_e32 v98, 2, v98
	ds_bpermute_b32 v98, v98, v106
	v_cmp_lt_i32_e32 vcc, v228, v222
	s_waitcnt lgkmcnt(0)
	v_add_f32_e32 v98, v106, v98
	v_cndmask_b32_e32 v99, v221, v228, vcc
	v_lshlrev_b32_e32 v99, 2, v99
	ds_bpermute_b32 v99, v99, v98
	s_waitcnt lgkmcnt(0)
	v_add_f32_e32 v247, v98, v99
.LBB0_729:
.LBB0_730:
	v_add_u32_e32 v116, 0x80, v200
	v_ashrrev_i32_e32 v117, 31, v116
	s_waitcnt lgkmcnt(0)
	v_lshlrev_b64 v[98:99], 11, v[116:117]
	v_lshl_add_u64 v[114:115], v[210:211], 0, v[98:99]
	v_add_u32_e32 v112, 0x90, v200
	global_load_dwordx4 v[118:121], v[114:115], off
	v_ashrrev_i32_e32 v113, 31, v112
	v_lshlrev_b64 v[98:99], 11, v[112:113]
	v_lshl_add_u64 v[110:111], v[210:211], 0, v[98:99]
	global_load_dwordx4 v[106:109], v[114:115], off offset:256
	global_load_dwordx4 v[102:105], v[110:111], off
	global_load_dwordx4 v[98:101], v[110:111], off offset:256
	s_and_b64 vcc, exec, s[6:7]
	s_mov_b64 s[20:21], -1
	s_waitcnt vmcnt(3)
	v_lshlrev_b32_e32 v122, 16, v118
	v_and_b32_e32 v123, 0xffff0000, v118
	v_lshlrev_b32_e32 v118, 16, v119
	v_and_b32_e32 v119, 0xffff0000, v119
	v_lshlrev_b32_e32 v124, 16, v120
	v_and_b32_e32 v125, 0xffff0000, v120
	v_lshlrev_b32_e32 v120, 16, v121
	v_and_b32_e32 v121, 0xffff0000, v121
	v_pk_mul_f32 v[122:123], v[90:91], v[122:123]
	v_pk_mul_f32 v[118:119], v[92:93], v[118:119]
	v_pk_mul_f32 v[124:125], v[94:95], v[124:125]
	v_pk_mul_f32 v[120:121], v[96:97], v[120:121]
	v_pk_fma_f32 v[80:81], v[80:81], v[206:207], v[118:119]
	v_pk_fma_f32 v[78:79], v[78:79], v[208:209], v[122:123]
	v_pk_fma_f32 v[76:77], v[76:77], v[202:203], v[120:121]
	v_pk_fma_f32 v[74:75], v[74:75], v[204:205], v[124:125]
	s_cbranch_vccnz .LBB0_732
	v_mov_b32_e32 v120, v79
	v_mov_b32_e32 v121, v75
	v_mov_b32_e32 v118, v78
	v_mov_b32_e32 v119, v74
	v_pk_mul_f32 v[120:121], v[120:121], v[120:121]
	v_mov_b32_e32 v122, v81
	v_mov_b32_e32 v123, v77
	v_pk_fma_f32 v[118:119], v[118:119], v[118:119], v[120:121]
	v_mov_b32_e32 v120, v80
	v_mov_b32_e32 v121, v76
	v_pk_mul_f32 v[122:123], v[122:123], v[122:123]
	v_pk_mul_f32 v[124:125], v[68:69], v[76:77]
	v_pk_fma_f32 v[120:121], v[120:121], v[120:121], v[122:123]
	v_pk_mul_f32 v[122:123], v[72:73], v[80:81]
	v_pk_add_f32 v[118:119], v[118:119], v[120:121]
	v_pk_mul_f32 v[120:121], v[70:71], v[78:79]
	v_pk_mul_f32 v[126:127], v[66:67], v[74:75]
	v_add_f32_e32 v118, v118, v119
	v_cvt_pk_bf16_f32 v120, v120, v121
	v_cvt_pk_bf16_f32 v121, v122, v123
	v_cvt_pk_bf16_f32 v122, v126, v127
	v_cvt_pk_bf16_f32 v123, v124, v125
	s_mov_b64 s[20:21], 0
	global_store_dwordx4 v[114:115], v[120:123], off

.LBB0_739:
	v_cmp_lt_i32_e32 vcc, v227, v222
	s_nop 1
	v_cndmask_b32_e32 v50, v221, v227, vcc
	v_lshlrev_b32_e32 v50, 2, v50
	ds_bpermute_b32 v50, v50, v74
	v_cmp_lt_i32_e32 vcc, v228, v222
	s_waitcnt lgkmcnt(0)
	v_add_f32_e32 v50, v74, v50
	v_cndmask_b32_e32 v51, v221, v228, vcc
	v_lshlrev_b32_e32 v51, 2, v51
	ds_bpermute_b32 v51, v51, v50
	s_waitcnt lgkmcnt(0)
	v_add_f32_e32 v248, v50, v51
.LBB0_741:
.LBB0_742:
	s_waitcnt vmcnt(1)
	v_lshlrev_b32_e32 v50, 16, v102
	s_waitcnt lgkmcnt(0)
	v_and_b32_e32 v51, 0xffff0000, v102
	v_lshlrev_b32_e32 v52, 16, v103
	v_and_b32_e32 v53, 0xffff0000, v103
	v_lshlrev_b32_e32 v54, 16, v104
	v_and_b32_e32 v55, 0xffff0000, v104
	v_lshlrev_b32_e32 v56, 16, v105
	v_and_b32_e32 v57, 0xffff0000, v105
	v_pk_mul_f32 v[50:51], v[90:91], v[50:51]
	v_pk_mul_f32 v[52:53], v[92:93], v[52:53]
	v_pk_mul_f32 v[54:55], v[94:95], v[54:55]
	v_pk_mul_f32 v[56:57], v[96:97], v[56:57]
	v_pk_fma_f32 v[48:49], v[48:49], v[206:207], v[52:53]
	v_pk_fma_f32 v[46:47], v[46:47], v[208:209], v[50:51]
	v_pk_fma_f32 v[44:45], v[44:45], v[202:203], v[56:57]
	v_pk_fma_f32 v[42:43], v[42:43], v[204:205], v[54:55]
	s_and_b64 vcc, exec, s[6:7]
	s_mov_b64 s[20:21], -1
	s_cbranch_vccnz .LBB0_744
	v_mov_b32_e32 v52, v47
	v_mov_b32_e32 v53, v43
	v_mov_b32_e32 v50, v46
	v_mov_b32_e32 v51, v42
	v_pk_mul_f32 v[52:53], v[52:53], v[52:53]
	v_mov_b32_e32 v54, v49
	v_mov_b32_e32 v55, v45
	v_pk_fma_f32 v[50:51], v[50:51], v[50:51], v[52:53]
	v_mov_b32_e32 v52, v48
	v_mov_b32_e32 v53, v44
	v_pk_mul_f32 v[54:55], v[54:55], v[54:55]
	v_pk_mul_f32 v[74:75], v[68:69], v[44:45]
	v_pk_fma_f32 v[52:53], v[52:53], v[52:53], v[54:55]
	v_pk_mul_f32 v[54:55], v[70:71], v[46:47]
	v_pk_add_f32 v[50:51], v[50:51], v[52:53]
	v_pk_mul_f32 v[56:57], v[66:67], v[42:43]
	v_add_f32_e32 v52, v50, v51
	v_pk_mul_f32 v[50:51], v[72:73], v[48:49]
	v_cvt_pk_bf16_f32 v54, v54, v55
	v_cvt_pk_bf16_f32 v55, v50, v51
	v_cvt_pk_bf16_f32 v56, v56, v57
	v_cvt_pk_bf16_f32 v57, v74, v75
	s_mov_b64 s[20:21], 0
	global_store_dwordx4 v[110:111], v[54:57], off

.LBB0_751:
	v_cmp_lt_i32_e32 vcc, v227, v222
	s_nop 1
	v_cndmask_b32_e32 v34, v221, v227, vcc
	v_lshlrev_b32_e32 v34, 2, v34
	ds_bpermute_b32 v34, v34, v42
	v_cmp_lt_i32_e32 vcc, v228, v222
	s_waitcnt lgkmcnt(0)
	v_add_f32_e32 v34, v42, v34
	v_cndmask_b32_e32 v35, v221, v228, vcc
	v_lshlrev_b32_e32 v35, 2, v35
	ds_bpermute_b32 v35, v35, v34
	s_waitcnt lgkmcnt(0)
	v_add_f32_e32 v249, v34, v35
.LBB0_753:
.LBB0_754:
	v_add_u32_e32 v52, 0xa0, v200
	v_ashrrev_i32_e32 v53, 31, v52
	s_waitcnt lgkmcnt(0)
	v_lshlrev_b64 v[34:35], 11, v[52:53]
	v_lshl_add_u64 v[50:51], v[210:211], 0, v[34:35]
	v_add_u32_e32 v48, 0xb0, v200
	global_load_dwordx4 v[54:57], v[50:51], off
	v_ashrrev_i32_e32 v49, 31, v48
	v_lshlrev_b64 v[34:35], 11, v[48:49]
	v_lshl_add_u64 v[46:47], v[210:211], 0, v[34:35]
	global_load_dwordx4 v[42:45], v[50:51], off offset:256
	global_load_dwordx4 v[38:41], v[46:47], off
	global_load_dwordx4 v[34:37], v[46:47], off offset:256
	s_and_b64 vcc, exec, s[6:7]
	s_mov_b64 s[20:21], -1
	s_waitcnt vmcnt(3)
	v_lshlrev_b32_e32 v74, 16, v54
	v_and_b32_e32 v75, 0xffff0000, v54
	v_lshlrev_b32_e32 v54, 16, v55
	v_and_b32_e32 v55, 0xffff0000, v55
	v_lshlrev_b32_e32 v76, 16, v56
	v_and_b32_e32 v77, 0xffff0000, v56
	v_lshlrev_b32_e32 v56, 16, v57
	v_and_b32_e32 v57, 0xffff0000, v57
	v_pk_mul_f32 v[74:75], v[90:91], v[74:75]
	v_pk_mul_f32 v[54:55], v[92:93], v[54:55]
	v_pk_mul_f32 v[76:77], v[94:95], v[76:77]
	v_pk_mul_f32 v[56:57], v[96:97], v[56:57]
	v_pk_fma_f32 v[32:33], v[32:33], v[206:207], v[54:55]
	v_pk_fma_f32 v[30:31], v[30:31], v[208:209], v[74:75]
	v_pk_fma_f32 v[28:29], v[28:29], v[202:203], v[56:57]
	v_pk_fma_f32 v[26:27], v[26:27], v[204:205], v[76:77]
	s_cbranch_vccnz .LBB0_756
	v_mov_b32_e32 v56, v31
	v_mov_b32_e32 v57, v27
	v_mov_b32_e32 v54, v30
	v_mov_b32_e32 v55, v26
	v_pk_mul_f32 v[56:57], v[56:57], v[56:57]
	v_mov_b32_e32 v74, v33
	v_mov_b32_e32 v75, v29
	v_pk_fma_f32 v[54:55], v[54:55], v[54:55], v[56:57]
	v_mov_b32_e32 v56, v32
	v_mov_b32_e32 v57, v28
	v_pk_mul_f32 v[74:75], v[74:75], v[74:75]
	v_pk_mul_f32 v[78:79], v[68:69], v[28:29]
	v_pk_fma_f32 v[56:57], v[56:57], v[56:57], v[74:75]
	v_pk_mul_f32 v[74:75], v[70:71], v[30:31]
	v_pk_add_f32 v[54:55], v[54:55], v[56:57]
	v_pk_mul_f32 v[56:57], v[72:73], v[32:33]
	v_pk_mul_f32 v[76:77], v[66:67], v[26:27]
	v_add_f32_e32 v54, v54, v55
	v_cvt_pk_bf16_f32 v74, v74, v75
	v_cvt_pk_bf16_f32 v75, v56, v57
	v_cvt_pk_bf16_f32 v76, v76, v77
	v_cvt_pk_bf16_f32 v77, v78, v79
	s_mov_b64 s[20:21], 0
	global_store_dwordx4 v[50:51], v[74:77], off

.LBB0_763:
	v_cmp_lt_i32_e32 vcc, v227, v222
	s_nop 1
	v_cndmask_b32_e32 v18, v221, v227, vcc
	v_lshlrev_b32_e32 v18, 2, v18
	ds_bpermute_b32 v18, v18, v26
	v_cmp_lt_i32_e32 vcc, v228, v222
	s_waitcnt lgkmcnt(0)
	v_add_f32_e32 v18, v26, v18
	v_cndmask_b32_e32 v19, v221, v228, vcc
	v_lshlrev_b32_e32 v19, 2, v19
	ds_bpermute_b32 v19, v19, v18
	s_waitcnt lgkmcnt(0)
	v_add_f32_e32 v250, v18, v19
.LBB0_765:
.LBB0_766:
	s_waitcnt vmcnt(1)
	v_lshlrev_b32_e32 v18, 16, v38
	s_waitcnt lgkmcnt(0)
	v_and_b32_e32 v19, 0xffff0000, v38
	v_lshlrev_b32_e32 v20, 16, v39
	v_and_b32_e32 v21, 0xffff0000, v39
	v_lshlrev_b32_e32 v22, 16, v40
	v_and_b32_e32 v23, 0xffff0000, v40
	v_lshlrev_b32_e32 v24, 16, v41
	v_and_b32_e32 v25, 0xffff0000, v41
	v_pk_mul_f32 v[18:19], v[90:91], v[18:19]
	v_pk_mul_f32 v[20:21], v[92:93], v[20:21]
	v_pk_mul_f32 v[22:23], v[94:95], v[22:23]
	v_pk_mul_f32 v[24:25], v[96:97], v[24:25]
	v_pk_fma_f32 v[16:17], v[16:17], v[206:207], v[20:21]
	v_pk_fma_f32 v[14:15], v[14:15], v[208:209], v[18:19]
	v_pk_fma_f32 v[12:13], v[12:13], v[202:203], v[24:25]
	v_pk_fma_f32 v[10:11], v[10:11], v[204:205], v[22:23]
	s_and_b64 vcc, exec, s[6:7]
	s_mov_b64 s[20:21], -1
	s_cbranch_vccnz .LBB0_768
	v_mov_b32_e32 v20, v15
	v_mov_b32_e32 v21, v11
	v_mov_b32_e32 v18, v14
	v_mov_b32_e32 v19, v10
	v_pk_mul_f32 v[20:21], v[20:21], v[20:21]
	v_mov_b32_e32 v22, v17
	v_mov_b32_e32 v23, v13
	v_pk_fma_f32 v[18:19], v[18:19], v[18:19], v[20:21]
	v_mov_b32_e32 v20, v16
	v_mov_b32_e32 v21, v12
	v_pk_mul_f32 v[22:23], v[22:23], v[22:23]
	v_pk_mul_f32 v[26:27], v[68:69], v[12:13]
	v_pk_fma_f32 v[20:21], v[20:21], v[20:21], v[22:23]
	v_pk_mul_f32 v[22:23], v[70:71], v[14:15]
	v_pk_add_f32 v[18:19], v[18:19], v[20:21]
	v_pk_mul_f32 v[24:25], v[66:67], v[10:11]
	v_add_f32_e32 v20, v18, v19
	v_pk_mul_f32 v[18:19], v[72:73], v[16:17]
	v_cvt_pk_bf16_f32 v22, v22, v23
	v_cvt_pk_bf16_f32 v23, v18, v19
	v_cvt_pk_bf16_f32 v24, v24, v25
	v_cvt_pk_bf16_f32 v25, v26, v27
	s_mov_b64 s[20:21], 0
	global_store_dwordx4 v[46:47], v[22:25], off

.LBB0_773:
	v_cmp_lt_i32_e32 vcc, v227, v222
	s_nop 1
	v_cndmask_b32_e32 v2, v221, v227, vcc
	v_lshlrev_b32_e32 v2, 2, v2
	ds_bpermute_b32 v2, v2, v10
	v_cmp_lt_i32_e32 vcc, v228, v222
	s_waitcnt lgkmcnt(0)
	v_add_f32_e32 v2, v10, v2
	v_cndmask_b32_e32 v3, v221, v228, vcc
	v_lshlrev_b32_e32 v3, 2, v3
	ds_bpermute_b32 v3, v3, v2
	s_and_saveexec_b64 s[6:7], s[8:9]
	s_cbranch_execz .LBB0_775
	v_lshl_add_u64 v[4:5], v[200:201], 2, s[58:59]
	s_waitcnt lgkmcnt(0)
	v_add_f32_e32 v2, v2, v3
	global_atomic_add_f32 v[4:5], v244, off
	global_atomic_add_f32 v[4:5], v245, off offset:64
	global_atomic_add_f32 v[4:5], v246, off offset:128
	global_atomic_add_f32 v[4:5], v247, off offset:192
	global_atomic_add_f32 v[4:5], v248, off offset:512
	global_atomic_add_f32 v[4:5], v249, off offset:576
	global_atomic_add_f32 v[4:5], v250, off offset:640
	global_atomic_add_f32 v[4:5], v2, off offset:704
